# prompt attention PV: V-fragment LDS reads hoisted ahead of the softmax
# baseline (speedup 1.0000x reference)
; __device__ __forceinline__ void attn_prompt_unit(const PP P, LAS unsigned char* lds, int b, int h, int qt) {
;     ...
;     for (int kt = 0; kt < nt_blk; ++kt) {
;         const bool more = kt + 1 < nt_blk;
;         if (more) { rk = *(const u32x4*)(gk + (size_t)(kt + 1) * 64 * 512); rv = *(const u32x4*)(gv + (kt + 1) * 64); if (tid < 256) rp = *(const u32x4*)(gp + (size_t)(kt + 1) * 64 * 32); }
;         if (kt < nt_w) {
;             const LAS unsigned char* kb = lds + (kt & 1) * AT_STAGE; const LAS unsigned char* vb = kb + AT_V;
;             f32x4 s[2][4];
; #pragma unroll
;             for (int sb = 0; sb < 4; ++sb) { s[0][sb] = (f32x4){0.f, 0.f, 0.f, 0.f}; s[1][sb] = (f32x4){0.f, 0.f, 0.f, 0.f};
; #pragma unroll
;                 for (int ks = 0; ks < 3; ++ks) { const bf16x8 kf = *(const LAS bf16x8*)(kb + (16 * sb + fr) * AT_KROW + ks * 64 + fq * 16);
;                     s[0][sb] = mfma16(kf, Qb[0][ks], s[0][sb]); s[1][sb] = mfma16(kf, Qb[1][ks], s[1][sb]); } }
;             bf16x8 Pb[2][2];
; #pragma unroll
;             for (int g = 0; g < 2; ++g) {
;                 float mx = -INFINITY;
; #pragma unroll
;                 for (int sb = 0; sb < 4; ++sb) mx = fmaxf(mx, fmaxf(fmaxf(s[g][sb][0], s[g][sb][1]), fmaxf(s[g][sb][2], s[g][sb][3])));
;                 mx = fmaxf(mx, xor16_get(mx)); mx = xor32_max(mx);
;                 const float mnew = fmaxf(m[g], mx), alpha = __builtin_amdgcn_exp2f(m[g] - mnew); m[g] = mnew;
;                 float ps = 0.f; float p[4][4];
; #pragma unroll
;                 for (int sb = 0; sb < 4; ++sb)
; #pragma unroll
;                     for (int j = 0; j < 4; ++j) { p[sb][j] = __builtin_amdgcn_exp2f(s[g][sb][j] - mnew); ps += p[sb][j]; }
;                 lsum[g] = lsum[g] * alpha + ps;
; #pragma unroll
;                 for (int kk = 0; kk < 2; ++kk) { u32x4 pw; pw.x = pk2(p[2 * kk][0], p[2 * kk][1]); pw.y = pk2(p[2 * kk][2], p[2 * kk][3]); pw.z = pk2(p[2 * kk + 1][0], p[2 * kk + 1][1]); pw.w = pk2(p[2 * kk + 1][2], p[2 * kk + 1][3]);
;                     Pb[g][kk] = __builtin_bit_cast(bf16x8, pw); }
; #pragma unroll
;                 for (int nt = 0; nt < 4; ++nt) O[g][nt] = O[g][nt] * alpha;
;             }
; #pragma unroll
;             for (int nt = 0; nt < 4; ++nt)
; #pragma unroll
;                 for (int kk = 0; kk < 2; ++kk) { const LAS unsigned char* vp = vb + (16 * nt + fr) * AT_VROW + kk * 64 + fq * 8;
.LBB0_44:
	s_or_b64 exec, exec, s[2:3]
	v_cmp_le_i32_e32 vcc, s26, v121
	s_and_saveexec_b64 s[2:3], vcc
	s_cbranch_execz .LBB0_46
	s_bitcmp1_b32 s26, 0
	s_cselect_b32 s27, 0x5800, 0
	s_add_i32 s27, s27, 0
	v_add3_u32 v73, s27, v98, v147
	ds_read_b128 v[200:203], v73
	ds_read_b128 v[204:207], v73 offset:64
	ds_read_b128 v[208:211], v73 offset:128
	ds_read_b128 v[212:215], v73 offset:3328
	ds_read_b128 v[216:219], v73 offset:3392
	ds_read_b128 v[220:223], v73 offset:3456
	ds_read_b128 v[224:227], v73 offset:6656
	ds_read_b128 v[228:231], v73 offset:6720
	ds_read_b128 v[232:235], v73 offset:6784
	ds_read_b128 v[236:239], v73 offset:9984
	ds_read_b128 v[240:243], v73 offset:10048
	ds_read_b128 v[244:247], v73 offset:10112
	s_waitcnt lgkmcnt(11)
	v_mfma_f32_16x16x32_bf16 v[154:157], v[200:203], v[40:43], 0
	v_mfma_f32_16x16x32_bf16 v[80:83], v[200:203], v[28:31], 0
	s_waitcnt lgkmcnt(10)
	v_mfma_f32_16x16x32_bf16 v[154:157], v[204:207], v[36:39], v[154:157]
	v_mfma_f32_16x16x32_bf16 v[80:83], v[204:207], v[20:23], v[80:83]
	s_waitcnt lgkmcnt(9)
	v_mfma_f32_16x16x32_bf16 v[154:157], v[208:211], v[32:35], v[154:157]
	v_mfma_f32_16x16x32_bf16 v[80:83], v[208:211], v[16:19], v[80:83]
	s_waitcnt lgkmcnt(8)
	v_mfma_f32_16x16x32_bf16 v[158:161], v[212:215], v[40:43], 0
	v_mfma_f32_16x16x32_bf16 v[84:87], v[212:215], v[28:31], 0
	s_waitcnt lgkmcnt(7)
	v_mfma_f32_16x16x32_bf16 v[158:161], v[216:219], v[36:39], v[158:161]
	v_mfma_f32_16x16x32_bf16 v[84:87], v[216:219], v[20:23], v[84:87]
	s_waitcnt lgkmcnt(6)
	v_mfma_f32_16x16x32_bf16 v[158:161], v[220:223], v[32:35], v[158:161]
	v_mfma_f32_16x16x32_bf16 v[84:87], v[220:223], v[16:19], v[84:87]
	s_waitcnt lgkmcnt(5)
	v_mfma_f32_16x16x32_bf16 v[178:181], v[224:227], v[40:43], 0
	v_mfma_f32_16x16x32_bf16 v[88:91], v[224:227], v[28:31], 0
	s_waitcnt lgkmcnt(4)
	v_mfma_f32_16x16x32_bf16 v[178:181], v[228:231], v[36:39], v[178:181]
	v_mfma_f32_16x16x32_bf16 v[88:91], v[228:231], v[20:23], v[88:91]
	s_waitcnt lgkmcnt(3)
	v_mfma_f32_16x16x32_bf16 v[178:181], v[232:235], v[32:35], v[178:181]
	v_mfma_f32_16x16x32_bf16 v[88:91], v[232:235], v[16:19], v[88:91]
	s_waitcnt lgkmcnt(2)
	v_mfma_f32_16x16x32_bf16 v[182:185], v[236:239], v[40:43], 0
	v_mfma_f32_16x16x32_bf16 v[92:95], v[236:239], v[28:31], 0
	s_waitcnt lgkmcnt(1)
	v_mfma_f32_16x16x32_bf16 v[182:185], v[240:243], v[36:39], v[182:185]
	v_mfma_f32_16x16x32_bf16 v[92:95], v[240:243], v[20:23], v[92:95]
	s_waitcnt lgkmcnt(0)
	v_mfma_f32_16x16x32_bf16 v[182:185], v[244:247], v[32:35], v[182:185]
	v_mfma_f32_16x16x32_bf16 v[92:95], v[244:247], v[16:19], v[92:95]
	s_nop 7
	s_nop 1
	v_add3_u32 v248, s27, v96, v148
	v_add_u32_e32 v249, 0x3000, v248
	v_add_u32_e32 v250, 0x3800, v248
	v_add_u32_e32 v251, 0x4000, v248
	v_add_u32_e32 v252, 0x4800, v248
	ds_read2_b64 v[200:203], v249 offset0:128 offset1:132
	ds_read2_b64 v[204:207], v249 offset0:136 offset1:140
	ds_read2_b64 v[208:211], v250 offset0:160 offset1:164
	ds_read2_b64 v[212:215], v250 offset0:168 offset1:172
	ds_read2_b64 v[216:219], v251 offset0:192 offset1:196
	ds_read2_b64 v[220:223], v251 offset0:200 offset1:204
	ds_read2_b64 v[224:227], v252 offset0:224 offset1:228
	ds_read2_b64 v[228:231], v252 offset0:232 offset1:236
	v_max_f32_e32 v125, v83, v83
	v_max_f32_e32 v73, v157, v157
	v_max_f32_e32 v139, v86, v86
	s_nop 1
	v_max_f32_e32 v74, v156, v156
	v_max_f32_e32 v73, v74, v73
	v_max_f32_e32 v74, v161, v161
	v_max_f32_e32 v75, v160, v160
	v_max_f32_e32 v74, v75, v74
	v_max3_f32 v73, v154, v155, v73
	v_max3_f32 v74, v158, v159, v74
	v_max3_f32 v73, v73, s37, v74
	v_max_f32_e32 v74, v181, v181
	v_max_f32_e32 v75, v180, v180
	v_max_f32_e32 v74, v75, v74
	v_max_f32_e32 v75, v185, v185
	v_max_f32_e32 v76, v184, v184
	v_max_f32_e32 v75, v76, v75
	v_max3_f32 v74, v178, v179, v74
	v_max3_f32 v75, v182, v183, v75
	v_max3_f32 v73, v73, v74, v75
	ds_swizzle_b32 v74, v73 offset:swizzle(SWAP,16)
	v_max_f32_e32 v141, v94, v94
	s_waitcnt lgkmcnt(0)
	v_max_f32_e32 v74, v74, v74
	v_max_f32_e32 v73, v73, v74
	v_mov_b32_e32 v74, v73
	s_nop 1
	v_permlane32_swap_b32_e32 v73, v74
	v_max3_f32 v123, v72, v73, v74
	v_sub_f32_e32 v72, v72, v123
	v_exp_f32_e32 v136, v72
	v_sub_f32_e32 v72, v154, v123
	v_exp_f32_e32 v138, v72
	v_sub_f32_e32 v72, v155, v123
	v_pk_mul_f32 v[46:47], v[46:47], v[136:137] op_sel_hi:[1,0]
	v_pk_mul_f32 v[44:45], v[44:45], v[136:137] op_sel_hi:[1,0]
	v_pk_mul_f32 v[54:55], v[54:55], v[136:137] op_sel_hi:[1,0]
	v_pk_mul_f32 v[52:53], v[52:53], v[136:137] op_sel_hi:[1,0]
	v_pk_mul_f32 v[58:59], v[58:59], v[136:137] op_sel_hi:[1,0]
	v_pk_mul_f32 v[56:57], v[56:57], v[136:137] op_sel_hi:[1,0]
	v_pk_mul_f32 v[70:71], v[70:71], v[136:137] op_sel_hi:[1,0]
	v_pk_mul_f32 v[68:69], v[68:69], v[136:137] op_sel_hi:[1,0]
	v_max_f32_e32 v137, v82, v82
	v_max_f32_e32 v125, v137, v125
	v_max_f32_e32 v137, v87, v87
	v_max_f32_e32 v137, v139, v137
	v_max3_f32 v125, v80, v81, v125
	v_max3_f32 v137, v84, v85, v137
	v_max3_f32 v125, v125, s37, v137
	v_max_f32_e32 v137, v91, v91
	v_max_f32_e32 v139, v90, v90
	v_max_f32_e32 v137, v139, v137
	v_max_f32_e32 v139, v95, v95
	v_max_f32_e32 v139, v141, v139
	v_max3_f32 v137, v88, v89, v137
	v_max3_f32 v139, v92, v93, v139
	v_max3_f32 v125, v125, v137, v139
	ds_swizzle_b32 v137, v125 offset:swizzle(SWAP,16)
	v_exp_f32_e32 v140, v72
	v_sub_f32_e32 v72, v156, v123
	v_exp_f32_e32 v154, v72
	v_sub_f32_e32 v72, v157, v123
	s_waitcnt lgkmcnt(0)
; #define LAS __attribute__((address_space(3)))
; __device__ __forceinline__ unsigned pk2(float lo, float hi) { const f32x2_ v = {lo, hi}; return __builtin_bit_cast(unsigned, __builtin_convertvector(v, bf16x2_)); }
; __device__ __forceinline__ f32x4 mfma16(bf16x8 a, bf16x8 b, f32x4 c) { return __builtin_amdgcn_mfma_f32_16x16x32_bf16(a, b, c, 0, 0, 0); }
; __device__ __forceinline__ void attn_prompt_unit(const PP P, LAS unsigned char* lds, int b, int h, int qt) {
;     ...
;                 const float mnew = fmaxf(m[g], mx), alpha = __builtin_amdgcn_exp2f(m[g] - mnew); m[g] = mnew;
;                 float ps = 0.f; float p[4][4];
; #pragma unroll
;                 for (int sb = 0; sb < 4; ++sb)
; #pragma unroll
;                     for (int j = 0; j < 4; ++j) { p[sb][j] = __builtin_amdgcn_exp2f(s[g][sb][j] - mnew); ps += p[sb][j]; }
;                 lsum[g] = lsum[g] * alpha + ps;
; #pragma unroll
;                 for (int kk = 0; kk < 2; ++kk) { u32x4 pw; pw.x = pk2(p[2 * kk][0], p[2 * kk][1]); pw.y = pk2(p[2 * kk][2], p[2 * kk][3]); pw.z = pk2(p[2 * kk + 1][0], p[2 * kk + 1][1]); pw.w = pk2(p[2 * kk + 1][2], p[2 * kk + 1][3]);
;                     Pb[g][kk] = __builtin_bit_cast(bf16x8, pw); }
; #pragma unroll
;                 for (int nt = 0; nt < 4; ++nt) O[g][nt] = O[g][nt] * alpha;
;             }
; #pragma unroll
;             for (int nt = 0; nt < 4; ++nt)
; #pragma unroll
;                 for (int kk = 0; kk < 2; ++kk) { const LAS unsigned char* vp = vb + (16 * nt + fr) * AT_VROW + kk * 64 + fq * 8;
;                     const s16x4 a = *(const LAS s16x4*)vp, c = *(const LAS s16x4*)(vp + 32);
;                     bf16x8 vf; vf[0] = a[0]; vf[1] = a[1]; vf[2] = a[2]; vf[3] = a[3]; vf[4] = c[0]; vf[5] = c[1]; vf[6] = c[2]; vf[7] = c[3];
;                     O[0][nt] = mfma16(vf, Pb[0][kk], O[0][nt]); O[1][nt] = mfma16(vf, Pb[1][kk], O[1][nt]); }
	v_max_f32_e32 v137, v137, v137
	v_max_f32_e32 v125, v125, v137
	v_mov_b32_e32 v137, v125
	s_nop 1
	v_permlane32_swap_b32_e32 v125, v137
	v_max3_f32 v125, v24, v125, v137
	v_sub_f32_e32 v24, v24, v125
	v_exp_f32_e32 v137, v24
	v_sub_f32_e32 v24, v80, v125
	v_exp_f32_e32 v139, v24
	v_sub_f32_e32 v24, v81, v125
	v_exp_f32_e32 v141, v24
	v_sub_f32_e32 v24, v82, v125
	v_exp_f32_e32 v155, v24
	v_sub_f32_e32 v24, v83, v125
	v_exp_f32_e32 v156, v72
	v_sub_f32_e32 v72, v158, v123
	v_exp_f32_e32 v157, v24
	v_sub_f32_e32 v24, v84, v125
	v_exp_f32_e32 v158, v72
	v_sub_f32_e32 v72, v159, v123
	v_exp_f32_e32 v159, v24
	v_sub_f32_e32 v24, v85, v125
	v_exp_f32_e32 v162, v72
	v_sub_f32_e32 v72, v160, v123
	v_exp_f32_e32 v163, v24
	v_sub_f32_e32 v24, v86, v125
	v_exp_f32_e32 v160, v72
	v_sub_f32_e32 v72, v161, v123
	v_exp_f32_e32 v161, v24
	v_sub_f32_e32 v24, v87, v125
	v_exp_f32_e32 v186, v72
	v_sub_f32_e32 v72, v178, v123
	v_exp_f32_e32 v187, v24
	v_sub_f32_e32 v24, v88, v125
	v_exp_f32_e32 v178, v72
	v_sub_f32_e32 v72, v179, v123
	v_exp_f32_e32 v179, v24
	v_sub_f32_e32 v24, v89, v125
	v_exp_f32_e32 v188, v72
	v_sub_f32_e32 v72, v180, v123
	v_exp_f32_e32 v189, v24
	v_sub_f32_e32 v24, v90, v125
	v_exp_f32_e32 v180, v72
	v_sub_f32_e32 v72, v181, v123
	v_exp_f32_e32 v181, v24
	v_sub_f32_e32 v24, v91, v125
	v_exp_f32_e32 v190, v72
	v_sub_f32_e32 v72, v182, v123
	v_exp_f32_e32 v191, v24
	v_sub_f32_e32 v24, v92, v125
	v_exp_f32_e32 v182, v72
	v_sub_f32_e32 v72, v183, v123
	v_exp_f32_e32 v183, v24
	v_sub_f32_e32 v24, v93, v125
	v_exp_f32_e32 v192, v72
	v_sub_f32_e32 v72, v184, v123
	v_exp_f32_e32 v193, v24
	v_sub_f32_e32 v24, v94, v125
	v_exp_f32_e32 v184, v72
	v_sub_f32_e32 v72, v185, v123
	v_exp_f32_e32 v185, v24
	v_sub_f32_e32 v24, v95, v125
	v_exp_f32_e32 v195, v24
	v_mov_b32_e32 v24, v137
	v_pk_mul_f32 v[6:7], v[6:7], v[24:25] op_sel_hi:[1,0]
	v_pk_mul_f32 v[4:5], v[4:5], v[24:25] op_sel_hi:[1,0]
	v_pk_mul_f32 v[2:3], v[2:3], v[24:25] op_sel_hi:[1,0]
	v_pk_mul_f32 v[0:1], v[0:1], v[24:25] op_sel_hi:[1,0]
	v_pk_mul_f32 v[10:11], v[10:11], v[24:25] op_sel_hi:[1,0]
	v_pk_mul_f32 v[8:9], v[8:9], v[24:25] op_sel_hi:[1,0]
	v_pk_mul_f32 v[14:15], v[14:15], v[24:25] op_sel_hi:[1,0]
	v_pk_mul_f32 v[12:13], v[12:13], v[24:25] op_sel_hi:[1,0]
	v_add3_u32 v24, s27, v96, v148
	v_add_u32_e32 v92, 0x3000, v24
	v_pk_add_f32 v[80:81], v[138:139], 0 op_sel_hi:[1,0]
	v_cvt_pk_bf16_f32 v76, v138, v140
	v_pk_add_f32 v[80:81], v[140:141], v[80:81]
	v_cvt_pk_bf16_f32 v77, v154, v156
	v_pk_add_f32 v[80:81], v[154:155], v[80:81]
	v_cvt_pk_bf16_f32 v78, v158, v162
	v_pk_add_f32 v[80:81], v[156:157], v[80:81]
	v_cvt_pk_bf16_f32 v79, v160, v186
	v_pk_add_f32 v[80:81], v[158:159], v[80:81]
	v_cvt_pk_bf16_f32 v84, v139, v141
	v_pk_add_f32 v[80:81], v[162:163], v[80:81]
	v_cvt_pk_bf16_f32 v85, v155, v157
	v_pk_add_f32 v[80:81], v[160:161], v[80:81]
	v_cvt_pk_bf16_f32 v86, v159, v163
	v_pk_add_f32 v[80:81], v[186:187], v[80:81]
	v_cvt_pk_bf16_f32 v87, v161, v187
	v_pk_add_f32 v[80:81], v[178:179], v[80:81]
	s_waitcnt lgkmcnt(0)
	v_mfma_f32_16x16x32_bf16 v[44:47], v[200:203], v[76:79], v[44:47]
	v_add_f32_e64 v80, v188, v80
	v_add_f32_e64 v81, v189, v81
	v_exp_f32_e32 v194, v72
	v_pk_add_f32 v[80:81], v[180:181], v[80:81]
	v_mfma_f32_16x16x32_bf16 v[4:7], v[200:203], v[84:87], v[4:7]
	v_pk_add_f32 v[80:81], v[190:191], v[80:81]
	v_cvt_pk_bf16_f32 v72, v178, v188
	v_pk_add_f32 v[80:81], v[182:183], v[80:81]
	v_cvt_pk_bf16_f32 v73, v180, v190
	v_pk_add_f32 v[80:81], v[192:193], v[80:81]
	v_cvt_pk_bf16_f32 v74, v182, v192
	v_pk_add_f32 v[80:81], v[184:185], v[80:81]
	v_cvt_pk_bf16_f32 v75, v184, v194
	v_pk_add_f32 v[80:81], v[194:195], v[80:81]
	v_cvt_pk_bf16_f32 v82, v183, v193
	v_pk_fma_f32 v[130:131], v[130:131], v[136:137], v[80:81]
	v_cvt_pk_bf16_f32 v80, v179, v189
	v_cvt_pk_bf16_f32 v81, v181, v191
	v_cvt_pk_bf16_f32 v83, v185, v195
	v_add_u32_e32 v92, 0x3800, v24
	s_waitcnt lgkmcnt(0)
	v_mfma_f32_16x16x32_bf16 v[44:47], v[204:207], v[72:75], v[44:47]
	v_mfma_f32_16x16x32_bf16 v[4:7], v[204:207], v[80:83], v[4:7]
	s_waitcnt lgkmcnt(0)
	v_mfma_f32_16x16x32_bf16 v[52:55], v[208:211], v[76:79], v[52:55]
	v_mfma_f32_16x16x32_bf16 v[0:3], v[208:211], v[84:87], v[0:3]
	v_add_u32_e32 v92, 0x4000, v24
	v_add_u32_e32 v24, 0x4800, v24
	s_waitcnt lgkmcnt(0)
	v_mfma_f32_16x16x32_bf16 v[52:55], v[212:215], v[72:75], v[52:55]
	v_mfma_f32_16x16x32_bf16 v[0:3], v[212:215], v[80:83], v[0:3]
	s_waitcnt lgkmcnt(0)
	v_mfma_f32_16x16x32_bf16 v[56:59], v[216:219], v[76:79], v[56:59]
	v_mfma_f32_16x16x32_bf16 v[8:11], v[216:219], v[84:87], v[8:11]
	s_waitcnt lgkmcnt(0)
	v_mfma_f32_16x16x32_bf16 v[56:59], v[220:223], v[72:75], v[56:59]
	v_mfma_f32_16x16x32_bf16 v[8:11], v[220:223], v[80:83], v[8:11]
	s_waitcnt lgkmcnt(0)
	v_mfma_f32_16x16x32_bf16 v[68:71], v[224:227], v[76:79], v[68:71]
	v_mov_b32_e32 v24, v125
	v_mfma_f32_16x16x32_bf16 v[12:15], v[224:227], v[84:87], v[12:15]
	s_waitcnt lgkmcnt(0)
	v_mfma_f32_16x16x32_bf16 v[68:71], v[228:231], v[72:75], v[68:71]
	v_mov_b32_e32 v72, v123
	v_mfma_f32_16x16x32_bf16 v[12:15], v[228:231], v[80:83], v[12:15]
